# R2 row loop: loop-top vmcnt waits removed (rows already waited at the latch; they only forced store acks), one wait in the preheader, explicit wait on layer-0 f32 row loads
# baseline (speedup 1.0000x reference)
; #define GAS __attribute__((address_space(1)))
; #define LAS __attribute__((address_space(3)))
; __device__ __forceinline__ float row16_max(float v) { v = fmaxf(v, dpp_f<0xB1>(v)); v = fmaxf(v, dpp_f<0x4E>(v)); v = fmaxf(v, dpp_f<0x141>(v)); v = fmaxf(v, dpp_f<0x140>(v)); return v; }
; __device__ __forceinline__ void p_r2(const Args& a, LAS unsigned char* lds, volatile LAS unsigned* MISC, int l, int wg, int G, int wave, int lane, int tid) {
;     ...
;     for (int chunk = wg; chunk < T / 256; chunk += G) {
;         if (tid < 32) MISC[MW_HIST + tid] = 0u;
;         { const int bch = (256 * chunk) / SEQ; const float* mbc = mods + ((size_t)l * BATCH + bch) * 6 * D; LAS f32x4* PV = (LAS f32x4*)(lds + R2_PAR);
;           for (int i = tid; i < 5 * 256; i += 512) { const int v = i >> 8, q = i & 255; const float* src = v == 0 ? mbc + 2 * D : v == 1 ? l1g : v == 2 ? l1b : v == 3 ? mbc + 4 * D : mbc + 3 * D; PV[i] = *(const GAS f32x4*)(src + 4 * q); } }
;         __syncthreads();
;         RowRaw xpre[2], mpre[2];
; #pragma unroll
;         for (int r = 0; r < 2; ++r) { const size_t o = (size_t)(256 * chunk + 2 * wave + r) * D; load_row_raw(MIX + o, lane, mpre[r]); if (l != 0) load_row_raw(xbf + o, lane, xpre[r]); else { xpre[r].w[0] = xpre[r].w[1] = (v4u){0u, 0u, 0u, 0u}; } }
;         for (int it = 0; it < 16; ++it) {
;     ...
;               for (int k = 0; k < 4; ++k) { float mx = row16_max(lg); mx = fmaxf(mx, __shfl_xor(mx, 16)); const unsigned long long bal = __ballot(lg == mx);
.LBB0_822:
	v_and_b32_e32 v18, 64, v237
	v_xor_b32_e32 v17, 16, v237
	v_add_u32_e32 v18, 64, v18
	v_cmp_lt_i32_e32 vcc, v17, v18
	s_mov_b32 s37, 0
	v_mov_b32_e32 v185, v171
	v_cndmask_b32_e32 v17, v237, v17, vcc
	v_lshlrev_b32_e32 v17, 2, v17
	s_waitcnt vmcnt(0)
	s_branch .LBB0_824

; __device__ __forceinline__ unsigned dpp_swap1(unsigned v) { return (unsigned)__builtin_amdgcn_update_dpp(0, (int)v, 0xB1, 0xF, 0xF, true); }
; __device__ __forceinline__ void unpack_row_raw(const RowRaw& r, int lane, v2u (&o)[4]) {
;     const bool odd = (lane & 1) != 0;
; #pragma unroll
;     for (int pr = 0; pr < 2; ++pr) { const v4u w = r.w[pr]; const v2u lo = (v2u){w.x, w.y}, hi = (v2u){w.z, w.w}, send = odd ? lo : hi; v2u recv; recv.x = dpp_swap1(send.x); recv.y = dpp_swap1(send.y);
;         o[2 * pr] = odd ? recv : lo; o[2 * pr + 1] = odd ? hi : recv; }
; }
; __device__ __forceinline__ void p_r2(const Args& a, LAS unsigned char* lds, volatile LAS unsigned* MISC, int l, int wg, int G, int wave, int lane, int tid) {
;     ...
;         for (int it = 0; it < 16; ++it) {
;             const int tb = 256 * chunk + 16 * it, t0 = tb + 2 * wave, b = t0 / SEQ; const float* mb = mods + ((size_t)l * BATCH + b) * 6 * D;
;             f32x4 x[2][4], u[2][4]; v2u mw[2][4], ob[2][4]; unsigned uq[2][4];
; #pragma unroll
;             for (int r = 0; r < 2; ++r) {
;                 if (l == 0) load_row4(xin + (size_t)(t0 + r) * D, lane, x[r]);
;                 else { v2u xw[4]; unpack_row_raw(xpre[r], lane, xw);
; #pragma unroll
;                     for (int j = 0; j < 4; ++j) x[r][j] = (f32x4){bf_lo(xw[j].x), bf_hi(xw[j].x), bf_lo(xw[j].y), bf_hi(xw[j].y)}; }
;                 unpack_row_raw(mpre[r], lane, mw[r]); }
.LBB0_824:
	s_and_b64 vcc, exec, s[60:61]
	s_cbranch_vccz .LBB0_838
	v_cndmask_b32_e64 v18, v73, v75, s[44:45]
	v_cndmask_b32_e64 v19, v72, v74, s[44:45]
	v_cndmask_b32_e64 v90, v77, v79, s[44:45]
	v_cndmask_b32_e64 v91, v76, v78, s[44:45]
	v_mov_b32_dpp v19, v19 quad_perm:[1,0,3,2] row_mask:0xf bank_mask:0xf bound_ctrl:1
	v_mov_b32_dpp v18, v18 quad_perm:[1,0,3,2] row_mask:0xf bank_mask:0xf bound_ctrl:1
	v_mov_b32_dpp v91, v91 quad_perm:[1,0,3,2] row_mask:0xf bank_mask:0xf bound_ctrl:1
	v_mov_b32_dpp v90, v90 quad_perm:[1,0,3,2] row_mask:0xf bank_mask:0xf bound_ctrl:1
	v_cndmask_b32_e64 v88, v18, v73, s[44:45]
	v_cndmask_b32_e64 v89, v19, v72, s[44:45]
	v_cndmask_b32_e64 v18, v75, v18, s[44:45]
	v_cndmask_b32_e64 v19, v74, v19, s[44:45]
	v_cndmask_b32_e64 v92, v90, v77, s[44:45]
	v_cndmask_b32_e64 v93, v91, v76, s[44:45]
	v_cndmask_b32_e64 v90, v79, v90, s[44:45]
	v_cndmask_b32_e64 v91, v78, v91, s[44:45]
	v_lshlrev_b32_e32 v144, 16, v89
	v_and_b32_e32 v145, 0xffff0000, v89
	v_lshlrev_b32_e32 v146, 16, v88
	v_and_b32_e32 v147, 0xffff0000, v88
	v_lshlrev_b32_e32 v116, 16, v19
	v_and_b32_e32 v117, 0xffff0000, v19
	v_lshlrev_b32_e32 v118, 16, v18
	v_and_b32_e32 v119, 0xffff0000, v18
	v_lshlrev_b32_e32 v112, 16, v93
	v_and_b32_e32 v113, 0xffff0000, v93
	v_lshlrev_b32_e32 v114, 16, v92
	v_and_b32_e32 v115, 0xffff0000, v92
	v_lshlrev_b32_e32 v104, 16, v91
	v_and_b32_e32 v105, 0xffff0000, v91
	v_lshlrev_b32_e32 v106, 16, v90
	v_and_b32_e32 v107, 0xffff0000, v90
	s_add_i32 s8, s72, s37
	s_cbranch_execnz .LBB0_827

; __device__ __forceinline__ unsigned dpp_swap1(unsigned v) { return (unsigned)__builtin_amdgcn_update_dpp(0, (int)v, 0xB1, 0xF, 0xF, true); }
; __device__ __forceinline__ void unpack_row_raw(const RowRaw& r, int lane, v2u (&o)[4]) {
;     const bool odd = (lane & 1) != 0;
; #pragma unroll
;     for (int pr = 0; pr < 2; ++pr) { const v4u w = r.w[pr]; const v2u lo = (v2u){w.x, w.y}, hi = (v2u){w.z, w.w}, send = odd ? lo : hi; v2u recv; recv.x = dpp_swap1(send.x); recv.y = dpp_swap1(send.y);
;         o[2 * pr] = odd ? recv : lo; o[2 * pr + 1] = odd ? hi : recv; }
; }
; __device__ __forceinline__ void p_r2(const Args& a, LAS unsigned char* lds, volatile LAS unsigned* MISC, int l, int wg, int G, int wave, int lane, int tid) {
;     ...
;             for (int r = 0; r < 2; ++r) {
;                 if (l == 0) load_row4(xin + (size_t)(t0 + r) * D, lane, x[r]);
;                 else { v2u xw[4]; unpack_row_raw(xpre[r], lane, xw);
; #pragma unroll
;                     for (int j = 0; j < 4; ++j) x[r][j] = (f32x4){bf_lo(xw[j].x), bf_hi(xw[j].x), bf_lo(xw[j].y), bf_hi(xw[j].y)}; }
;                 unpack_row_raw(mpre[r], lane, mw[r]); }
;             if (it + 1 < 16) {
; #pragma unroll
;                 for (int r = 0; r < 2; ++r) { load_row_raw(MIX + (size_t)(t0 + 16 + r) * D, lane, mpre[r]); if (l != 0) load_row_raw(xbf + (size_t)(t0 + 16 + r) * D, lane, xpre[r]); } }
.LBB0_827:
	v_cndmask_b32_e64 v19, v125, v127, s[44:45]
	v_cndmask_b32_e64 v18, v124, v126, s[44:45]
	v_cndmask_b32_e64 v88, v121, v123, s[44:45]
	v_mov_b32_dpp v186, v19 quad_perm:[1,0,3,2] row_mask:0xf bank_mask:0xf bound_ctrl:1
	v_cndmask_b32_e64 v19, v120, v122, s[44:45]
	v_mov_b32_dpp v18, v18 quad_perm:[1,0,3,2] row_mask:0xf bank_mask:0xf bound_ctrl:1
	s_and_b64 vcc, exec, s[52:53]
	v_mov_b32_dpp v19, v19 quad_perm:[1,0,3,2] row_mask:0xf bank_mask:0xf bound_ctrl:1
	v_mov_b32_dpp v187, v88 quad_perm:[1,0,3,2] row_mask:0xf bank_mask:0xf bound_ctrl:1
	s_cbranch_vccnz .LBB0_839
	v_cndmask_b32_e64 v88, v81, v83, s[44:45]
	v_cndmask_b32_e64 v89, v80, v82, s[44:45]
	v_cndmask_b32_e64 v92, v85, v87, s[44:45]
	v_cndmask_b32_e64 v93, v84, v86, s[44:45]
	v_mov_b32_dpp v89, v89 quad_perm:[1,0,3,2] row_mask:0xf bank_mask:0xf bound_ctrl:1
	v_mov_b32_dpp v88, v88 quad_perm:[1,0,3,2] row_mask:0xf bank_mask:0xf bound_ctrl:1
	v_mov_b32_dpp v93, v93 quad_perm:[1,0,3,2] row_mask:0xf bank_mask:0xf bound_ctrl:1
	v_mov_b32_dpp v92, v92 quad_perm:[1,0,3,2] row_mask:0xf bank_mask:0xf bound_ctrl:1
	v_cndmask_b32_e64 v90, v88, v81, s[44:45]
	v_cndmask_b32_e64 v91, v89, v80, s[44:45]
	v_cndmask_b32_e64 v88, v83, v88, s[44:45]
	v_cndmask_b32_e64 v89, v82, v89, s[44:45]
	v_cndmask_b32_e64 v94, v92, v85, s[44:45]
	v_cndmask_b32_e64 v95, v93, v84, s[44:45]
	v_cndmask_b32_e64 v92, v87, v92, s[44:45]
	v_cndmask_b32_e64 v93, v86, v93, s[44:45]
	v_lshlrev_b32_e32 v148, 16, v91
	v_and_b32_e32 v149, 0xffff0000, v91
	v_lshlrev_b32_e32 v150, 16, v90
	v_and_b32_e32 v151, 0xffff0000, v90
	v_lshlrev_b32_e32 v140, 16, v89
	v_and_b32_e32 v141, 0xffff0000, v89
	v_lshlrev_b32_e32 v142, 16, v88
	v_and_b32_e32 v143, 0xffff0000, v88
	v_lshlrev_b32_e32 v128, 16, v95
	v_and_b32_e32 v129, 0xffff0000, v95
	v_lshlrev_b32_e32 v130, 16, v94
	v_and_b32_e32 v131, 0xffff0000, v94
	v_lshlrev_b32_e32 v108, 16, v93
	v_and_b32_e32 v109, 0xffff0000, v93
	v_lshlrev_b32_e32 v110, 16, v92
	v_and_b32_e32 v111, 0xffff0000, v92
	s_cbranch_execnz .LBB0_830
.LBB0_829:
	s_add_i32 s2, s8, 1
	s_ashr_i32 s3, s2, 31
	s_lshl_b64 s[2:3], s[2:3], 12
	v_lshl_add_u64 v[88:89], v[158:159], 0, s[2:3]
	global_load_dwordx4 v[148:151], v[88:89], off
	global_load_dwordx4 v[140:143], v[88:89], off offset:1024
	global_load_dwordx4 v[128:131], v[88:89], off offset:2048
	global_load_dwordx4 v[108:111], v[88:89], off offset:3072
	s_waitcnt vmcnt(0)
.LBB0_830:
	v_cndmask_b32_e64 v88, v137, v139, s[44:45]
	v_cndmask_b32_e64 v89, v136, v138, s[44:45]
	s_cmpk_lg_i32 s37, 0xf0
	v_mov_b32_dpp v190, v88 quad_perm:[1,0,3,2] row_mask:0xf bank_mask:0xf bound_ctrl:1
	v_mov_b32_dpp v188, v89 quad_perm:[1,0,3,2] row_mask:0xf bank_mask:0xf bound_ctrl:1
	v_cndmask_b32_e64 v88, v133, v135, s[44:45]
	v_cndmask_b32_e64 v89, v132, v134, s[44:45]
	s_nop 0
	v_mov_b32_dpp v191, v88 quad_perm:[1,0,3,2] row_mask:0xf bank_mask:0xf bound_ctrl:1
	v_mov_b32_dpp v189, v89 quad_perm:[1,0,3,2] row_mask:0xf bank_mask:0xf bound_ctrl:1
	s_cbranch_scc0 .LBB0_835
	s_add_i32 s2, s8, 16
	s_ashr_i32 s3, s2, 31
	s_lshl_b64 s[34:35], s[2:3], 11
	v_lshl_add_u64 v[88:89], v[152:153], 0, s[34:35]
	global_load_dwordx4 v[92:95], v[88:89], off
	s_nop 0
	global_load_dwordx4 v[88:91], v[88:89], off offset:1024
	s_and_b64 vcc, exec, s[60:61]
	s_cbranch_vccz .LBB0_833
	s_lshl_b64 s[2:3], s[2:3], 10
	v_lshl_add_u64 v[76:77], s[2:3], 1, v[154:155]
	global_load_dwordx4 v[72:75], v[76:77], off
	s_nop 0
	global_load_dwordx4 v[76:79], v[76:77], off offset:1024
